# v19 + LN2 (both layers): nt (streaming) hint on the per-token global loads and stores
# speedup vs baseline: 1.0068x; 1.0068x over previous
.LBB0_925:
	s_or_b64 exec, exec, s[0:1]
	v_mov_b32_e32 v36, v128
	s_waitcnt lgkmcnt(0)
	v_mov_b32_e32 v0, v128
	s_barrier
	v_readlane_b32 s0, v237, 56
	v_ashrrev_i32_e32 v0, 6, v0
	v_readlane_b32 s0, v237, 36
	v_readlane_b32 s2, v237, 58
	s_mov_b32 s11, 0x8000
	v_add_u32_e32 v40, s0, v0
	v_readlane_b32 s3, v237, 59
	s_lshl_b32 s96, s2, 2
	v_cmp_gt_i32_e32 vcc, s11, v40
	v_readlane_b32 s1, v237, 57
	s_and_saveexec_b64 s[2:3], vcc
	s_cbranch_execz .LBB0_928
	v_ashrrev_i32_e32 v41, 31, v40
	v_readlane_b32 s0, v237, 40
	v_lshlrev_b32_e32 v2, 2, v36
	v_lshlrev_b64 v[38:39], 11, v[40:41]
	v_readlane_b32 s1, v237, 41
	v_and_b32_e32 v4, 0xfc, v2
	v_lshlrev_b32_e32 v34, 1, v4
	v_lshl_add_u64 v[0:1], s[0:1], 0, v[38:39]
	v_mov_b32_e32 v35, 0
	v_lshl_add_u64 v[2:3], s[76:77], 0, v[38:39]
	v_readlane_b32 s12, v237, 48
	v_lshl_add_u64 v[0:1], v[0:1], 0, v[34:35]
	v_lshl_add_u64 v[2:3], v[2:3], 0, v[34:35]
	v_lshlrev_b32_e32 v28, 2, v4
	v_readlane_b32 s14, v237, 50
	v_readlane_b32 s15, v237, 51
	global_load_dwordx2 v[42:43], v[0:1], off offset:1536 nt
	global_load_dwordx2 v[44:45], v[0:1], off offset:1024 nt
	global_load_dwordx2 v[48:49], v[0:1], off offset:512 nt
	global_load_dwordx2 v[52:53], v[0:1], off nt
	global_load_dwordx2 v[46:47], v[2:3], off offset:1536 nt
	global_load_dwordx2 v[50:51], v[2:3], off offset:1024 nt
	global_load_dwordx2 v[54:55], v[2:3], off offset:512 nt
	global_load_dwordx2 v[56:57], v[2:3], off nt
	v_readlane_b32 s16, v237, 52
	v_readlane_b32 s17, v237, 53
	global_load_dwordx4 v[0:3], v28, s[14:15]
	s_nop 3
	global_load_dwordx4 v[4:7], v28, s[16:17]
	global_load_dwordx4 v[8:11], v28, s[14:15] offset:1024
	global_load_dwordx4 v[12:15], v28, s[16:17] offset:1024
	global_load_dwordx4 v[16:19], v28, s[14:15] offset:2048
	global_load_dwordx4 v[20:23], v28, s[16:17] offset:2048
	global_load_dwordx4 v[24:27], v28, s[14:15] offset:3072
	s_nop 0
	global_load_dwordx4 v[28:31], v28, s[16:17] offset:3072
	v_readlane_b32 s13, v237, 49
	s_waitcnt vmcnt(17)
	v_lshlrev_b64 v[58:59], 12, v[40:41]
	v_and_b32_e32 v41, 63, v36
	v_readlane_b32 s12, v237, 56
	v_lshl_or_b32 v38, v41, 3, v38
	v_readlane_b32 s13, v237, 57
	v_readlane_b32 s18, v237, 54
	v_readlane_b32 s19, v237, 55
	v_lshl_add_u64 v[32:33], s[76:77], 0, v[34:35]
	v_lshl_add_u64 v[34:35], s[0:1], 0, v[34:35]
	v_lshl_or_b32 v58, v41, 4, v58
	s_ashr_i32 s97, s96, 31
	v_lshl_add_u64 v[38:39], s[12:13], 0, v[38:39]
	s_mov_b64 s[0:1], 0xa500000
	v_lshl_add_u64 v[36:37], s[18:19], 0, v[58:59]
	s_lshl_b64 s[4:5], s[96:97], 12
	v_lshl_add_u64 v[38:39], v[38:39], 0, s[0:1]
	s_lshl_b64 s[6:7], s[96:97], 11
	s_mov_b64 s[8:9], 0
	s_movk_i32 s12, 0x7fff
	s_mov_b32 s10, 0x3fb504f3
	v_mov_b32_e32 v41, 0x3727c5ac
	s_mov_b32 s13, 0x800000
	v_readlane_b32 s14, v237, 58
	v_readlane_b32 s15, v237, 59
.LBB0_927:
	v_add_u32_e32 v81, s96, v40
	v_cmp_gt_i32_e64 s[0:1], s11, v81
	s_waitcnt vmcnt(8)
	v_lshlrev_b32_e32 v58, 16, v56
	v_and_b32_e32 v59, 0xffff0000, v56
	v_lshlrev_b32_e32 v56, 16, v57
	v_and_b32_e32 v57, 0xffff0000, v57
	v_lshlrev_b32_e32 v60, 16, v52
	v_and_b32_e32 v61, 0xffff0000, v52
	v_lshlrev_b32_e32 v52, 16, v53
	v_and_b32_e32 v53, 0xffff0000, v53
	v_lshlrev_b32_e32 v62, 16, v54
	v_and_b32_e32 v63, 0xffff0000, v54
	v_lshlrev_b32_e32 v54, 16, v55
	v_and_b32_e32 v55, 0xffff0000, v55
	v_lshlrev_b32_e32 v64, 16, v48
	v_and_b32_e32 v65, 0xffff0000, v48
	v_lshlrev_b32_e32 v48, 16, v49
	v_and_b32_e32 v49, 0xffff0000, v49
	v_lshlrev_b32_e32 v66, 16, v50
	v_and_b32_e32 v67, 0xffff0000, v50
	v_lshlrev_b32_e32 v68, 16, v44
	v_and_b32_e32 v69, 0xffff0000, v44
	v_lshlrev_b32_e32 v72, 16, v46
	v_and_b32_e32 v73, 0xffff0000, v46
	v_lshlrev_b32_e32 v76, 16, v42
	v_and_b32_e32 v77, 0xffff0000, v42
	v_cndmask_b32_e64 v80, v40, v81, s[0:1]
	v_lshlrev_b32_e32 v50, 16, v51
	v_and_b32_e32 v51, 0xffff0000, v51
	v_lshlrev_b32_e32 v70, 16, v45
	v_and_b32_e32 v71, 0xffff0000, v45
	v_lshlrev_b32_e32 v74, 16, v47
	v_and_b32_e32 v75, 0xffff0000, v47
	v_lshlrev_b32_e32 v78, 16, v43
	v_and_b32_e32 v79, 0xffff0000, v43
	v_cmp_lt_i32_e32 vcc, s12, v81
	v_pk_fma_f32 v[42:43], v[58:59], s[10:11], v[60:61] op_sel_hi:[1,0,1]
	v_pk_fma_f32 v[44:45], v[56:57], s[10:11], v[52:53] op_sel_hi:[1,0,1]
	v_pk_fma_f32 v[46:47], v[62:63], s[10:11], v[64:65] op_sel_hi:[1,0,1]
	v_pk_fma_f32 v[48:49], v[54:55], s[10:11], v[48:49] op_sel_hi:[1,0,1]
	v_pk_fma_f32 v[52:53], v[66:67], s[10:11], v[68:69] op_sel_hi:[1,0,1]
	v_pk_fma_f32 v[54:55], v[72:73], s[10:11], v[76:77] op_sel_hi:[1,0,1]
	v_mov_b32_e32 v40, v81
	v_ashrrev_i32_e32 v81, 31, v80
	v_pk_fma_f32 v[50:51], v[50:51], s[10:11], v[70:71] op_sel_hi:[1,0,1]
	v_pk_fma_f32 v[56:57], v[74:75], s[10:11], v[78:79] op_sel_hi:[1,0,1]
	v_mov_b32_e32 v58, v42
	v_mov_b32_e32 v59, v46
	v_mov_b32_e32 v60, v43
	v_mov_b32_e32 v61, v47
	v_mov_b32_e32 v66, v52
	v_mov_b32_e32 v67, v54
	v_mov_b32_e32 v68, v53
	v_mov_b32_e32 v69, v55
	v_lshlrev_b64 v[74:75], 11, v[80:81]
	v_mov_b32_e32 v62, v44
	v_mov_b32_e32 v63, v48
	v_mov_b32_e32 v70, v50
	v_mov_b32_e32 v71, v56
	v_pk_add_f32 v[58:59], v[58:59], v[60:61]
	v_pk_add_f32 v[60:61], v[66:67], v[68:69]
	v_lshl_add_u64 v[66:67], v[32:33], 0, v[74:75]
	v_lshl_add_u64 v[68:69], v[34:35], 0, v[74:75]
	v_pk_add_f32 v[58:59], v[62:63], v[58:59]
	v_pk_add_f32 v[60:61], v[70:71], v[60:61]
	global_load_dwordx2 v[62:63], v[66:67], off nt
	global_load_dwordx2 v[70:71], v[66:67], off offset:512 nt
	global_load_dwordx2 v[74:75], v[66:67], off offset:1024 nt
	s_nop 0
	global_load_dwordx2 v[66:67], v[66:67], off offset:1536 nt
	s_nop 0
	global_load_dwordx2 v[76:77], v[68:69], off nt
	global_load_dwordx2 v[78:79], v[68:69], off offset:512 nt
	global_load_dwordx2 v[80:81], v[68:69], off offset:1024 nt
	s_nop 0
	global_load_dwordx2 v[68:69], v[68:69], off offset:1536 nt
	v_mov_b32_e32 v64, v45
	v_mov_b32_e32 v65, v49
	v_pk_add_f32 v[58:59], v[64:65], v[58:59]
	v_mov_b32_e32 v72, v51
	v_mov_b32_e32 v73, v57
	v_add_f32_e32 v58, 0, v58
	v_pk_add_f32 v[60:61], v[72:73], v[60:61]
	v_add_f32_e32 v58, v58, v59
	v_add_f32_e32 v58, v58, v60
	v_add_f32_e32 v58, v58, v61
	s_or_b64 s[8:9], vcc, s[8:9]
	s_nop 0
	v_add_f32_dpp v58, v58, v58 quad_perm:[1,0,3,2] row_mask:0xf bank_mask:0xf bound_ctrl:1
	s_nop 1
	v_add_f32_dpp v58, v58, v58 quad_perm:[2,3,0,1] row_mask:0xf bank_mask:0xf bound_ctrl:1
	s_nop 1
	v_add_f32_dpp v58, v58, v58 row_half_mirror row_mask:0xf bank_mask:0xf bound_ctrl:1
	s_nop 1
	v_add_f32_dpp v58, v58, v58 row_mirror row_mask:0xf bank_mask:0xf bound_ctrl:1
	s_nop 0
	v_readlane_b32 s14, v58, 16
	v_readlane_b32 s15, v58, 48
	v_readlane_b32 s0, v58, 0
	v_readlane_b32 s1, v58, 32
	v_mov_b32_e32 v58, s14
	v_mov_b32_e32 v59, s15
	v_pk_add_f32 v[58:59], s[0:1], v[58:59]
	s_nop 0
	v_add_f32_e32 v58, v58, v59
	v_mul_f32_e32 v58, 0x3a800000, v58
	v_pk_add_f32 v[42:43], v[42:43], v[58:59] op_sel_hi:[1,0] neg_lo:[0,1] neg_hi:[0,1]
	v_pk_add_f32 v[44:45], v[44:45], v[58:59] op_sel_hi:[1,0] neg_lo:[0,1] neg_hi:[0,1]
	v_pk_add_f32 v[46:47], v[46:47], v[58:59] op_sel_hi:[1,0] neg_lo:[0,1] neg_hi:[0,1]
	v_pk_add_f32 v[48:49], v[48:49], v[58:59] op_sel_hi:[1,0] neg_lo:[0,1] neg_hi:[0,1]
	v_pk_add_f32 v[52:53], v[52:53], v[58:59] op_sel_hi:[1,0] neg_lo:[0,1] neg_hi:[0,1]
	v_pk_add_f32 v[50:51], v[50:51], v[58:59] op_sel_hi:[1,0] neg_lo:[0,1] neg_hi:[0,1]
	v_pk_add_f32 v[54:55], v[54:55], v[58:59] op_sel_hi:[1,0] neg_lo:[0,1] neg_hi:[0,1]
	v_pk_add_f32 v[56:57], v[56:57], v[58:59] op_sel_hi:[1,0] neg_lo:[0,1] neg_hi:[0,1]
	v_pk_mul_f32 v[58:59], v[42:43], v[42:43]
	v_pk_mul_f32 v[60:61], v[44:45], v[44:45]
	v_add_f32_e32 v58, v58, v59
	v_add_f32_e32 v58, v60, v58
	v_pk_mul_f32 v[64:65], v[46:47], v[46:47]
	v_add_f32_e32 v58, v61, v58
	v_add_f32_e32 v58, v64, v58
	v_pk_mul_f32 v[72:73], v[48:49], v[48:49]
	v_add_f32_e32 v58, v65, v58
	v_add_f32_e32 v58, v72, v58
	v_pk_mul_f32 v[82:83], v[52:53], v[52:53]
	v_add_f32_e32 v58, v73, v58
	v_add_f32_e32 v58, v82, v58
	v_pk_mul_f32 v[84:85], v[50:51], v[50:51]
	v_add_f32_e32 v58, v83, v58
	v_add_f32_e32 v58, v84, v58
	v_pk_mul_f32 v[86:87], v[54:55], v[54:55]
	v_add_f32_e32 v58, v85, v58
	v_add_f32_e32 v58, v86, v58
	v_pk_mul_f32 v[88:89], v[56:57], v[56:57]
	v_add_f32_e32 v58, v87, v58
	v_add_f32_e32 v58, v88, v58
	v_add_f32_e32 v58, v89, v58
	s_nop 1
	v_add_f32_dpp v58, v58, v58 quad_perm:[1,0,3,2] row_mask:0xf bank_mask:0xf bound_ctrl:1
	s_nop 1
	v_add_f32_dpp v58, v58, v58 quad_perm:[2,3,0,1] row_mask:0xf bank_mask:0xf bound_ctrl:1
	s_nop 1
	v_add_f32_dpp v58, v58, v58 row_half_mirror row_mask:0xf bank_mask:0xf bound_ctrl:1
	s_nop 1
	v_add_f32_dpp v58, v58, v58 row_mirror row_mask:0xf bank_mask:0xf bound_ctrl:1
	s_nop 0
	v_readlane_b32 s14, v58, 16
	v_readlane_b32 s15, v58, 48
	v_readlane_b32 s0, v58, 0
	v_readlane_b32 s1, v58, 32
	v_mov_b32_e32 v58, s14
	v_mov_b32_e32 v59, s15
	v_pk_add_f32 v[58:59], s[0:1], v[58:59]
	s_nop 0
	v_add_f32_e32 v58, v58, v59
	v_fmamk_f32 v58, v58, 0x3a800000, v41
	v_mul_f32_e32 v59, 0x4b800000, v58
	v_cmp_gt_f32_e32 vcc, s13, v58
	s_nop 1
	v_cndmask_b32_e32 v58, v58, v59, vcc
	v_rsq_f32_e32 v58, v58
	s_nop 0
	v_mul_f32_e32 v59, 0x45800000, v58
	v_cndmask_b32_e32 v58, v58, v59, vcc
	v_pk_mul_f32 v[42:43], v[42:43], v[58:59] op_sel_hi:[1,0]
	v_pk_mul_f32 v[44:45], v[44:45], v[58:59] op_sel_hi:[1,0]
	v_pk_mul_f32 v[46:47], v[46:47], v[58:59] op_sel_hi:[1,0]
	v_pk_mul_f32 v[48:49], v[48:49], v[58:59] op_sel_hi:[1,0]
	v_pk_mul_f32 v[52:53], v[52:53], v[58:59] op_sel_hi:[1,0]
	v_pk_mul_f32 v[60:61], v[50:51], v[58:59] op_sel_hi:[1,0]
	v_pk_mul_f32 v[54:55], v[54:55], v[58:59] op_sel_hi:[1,0]
	v_pk_mul_f32 v[56:57], v[56:57], v[58:59] op_sel_hi:[1,0]
	s_waitcnt vmcnt(14)
	v_pk_fma_f32 v[42:43], v[0:1], v[42:43], v[4:5]
	v_pk_fma_f32 v[44:45], v[2:3], v[44:45], v[6:7]
	s_waitcnt vmcnt(12)
	v_pk_fma_f32 v[46:47], v[8:9], v[46:47], v[12:13]
	v_pk_fma_f32 v[48:49], v[10:11], v[48:49], v[14:15]
	s_waitcnt vmcnt(10)
	v_pk_fma_f32 v[50:51], v[16:17], v[52:53], v[20:21]
	v_pk_fma_f32 v[52:53], v[18:19], v[60:61], v[22:23]
	s_waitcnt vmcnt(8)
	v_pk_fma_f32 v[54:55], v[24:25], v[54:55], v[28:29]
	v_pk_fma_f32 v[56:57], v[26:27], v[56:57], v[30:31]
	global_store_dwordx4 v[36:37], v[42:45], off nt
	global_store_dwordx4 v[36:37], v[46:49], off offset:1024 nt
	global_store_dwordx4 v[36:37], v[50:53], off offset:2048 nt
	v_cvt_pk_bf16_f32 v42, v42, v43
	v_cvt_pk_bf16_f32 v43, v44, v45
	v_cvt_pk_bf16_f32 v44, v46, v47
	v_cvt_pk_bf16_f32 v45, v48, v49
	v_cvt_pk_bf16_f32 v46, v50, v51
	v_cvt_pk_bf16_f32 v47, v52, v53
	v_cvt_pk_bf16_f32 v48, v54, v55
	v_cvt_pk_bf16_f32 v49, v56, v57
	global_store_dwordx4 v[36:37], v[54:57], off offset:3072 nt
	v_lshl_add_u64 v[36:37], v[36:37], 0, s[4:5]
	global_store_dwordx2 v[38:39], v[42:43], off nt
	global_store_dwordx2 v[38:39], v[44:45], off offset:512 nt
	global_store_dwordx2 v[38:39], v[46:47], off offset:1024 nt
	global_store_dwordx2 v[38:39], v[48:49], off offset:1536 nt
	v_lshl_add_u64 v[38:39], v[38:39], 0, s[6:7]
	s_waitcnt vmcnt(11)
	v_mov_b64_e32 v[52:53], v[76:77]
	s_waitcnt vmcnt(10)
	v_mov_b64_e32 v[48:49], v[78:79]
	s_waitcnt vmcnt(9)
	v_mov_b64_e32 v[44:45], v[80:81]
	s_waitcnt vmcnt(8)
	v_mov_b64_e32 v[42:43], v[68:69]
	v_mov_b64_e32 v[56:57], v[62:63]
	v_mov_b64_e32 v[54:55], v[70:71]
	v_mov_b64_e32 v[50:51], v[74:75]
	v_mov_b64_e32 v[46:47], v[66:67]
	s_andn2_b64 exec, exec, s[8:9]
	s_cbranch_execnz .LBB0_927

.LBB0_2049:
	s_or_b64 exec, exec, s[0:1]
	v_mov_b32_e32 v36, v128
	s_waitcnt lgkmcnt(0)
	s_barrier
	v_readlane_b32 s0, v237, 36
	v_ashrrev_i32_e32 v0, 6, v128
	s_mov_b32 s7, 0x8000
	v_add_u32_e32 v38, s0, v0
	v_cmp_gt_i32_e32 vcc, s7, v38
	s_and_saveexec_b64 s[0:1], vcc
	s_cbranch_execz .LBB0_2052
	v_ashrrev_i32_e32 v39, 31, v38
	v_lshlrev_b32_e32 v4, 2, v36
	v_lshlrev_b64 v[0:1], 11, v[38:39]
	v_and_b32_e32 v6, 0xfc, v4
	v_lshl_add_u64 v[2:3], s[56:57], 0, v[0:1]
	v_lshlrev_b32_e32 v4, 1, v6
	v_mov_b32_e32 v5, 0
	v_lshl_add_u64 v[0:1], s[76:77], 0, v[0:1]
	v_lshl_add_u64 v[2:3], v[2:3], 0, v[4:5]
	v_lshl_add_u64 v[0:1], v[0:1], 0, v[4:5]
	v_lshl_add_u64 v[32:33], s[76:77], 0, v[4:5]
	v_lshl_add_u64 v[34:35], s[56:57], 0, v[4:5]
	v_lshlrev_b32_e32 v4, 2, v6
	global_load_dwordx2 v[40:41], v[2:3], off offset:1536 nt
	global_load_dwordx2 v[42:43], v[2:3], off offset:1024 nt
	global_load_dwordx2 v[46:47], v[2:3], off offset:512 nt
	global_load_dwordx2 v[50:51], v[2:3], off nt
	global_load_dwordx2 v[44:45], v[0:1], off offset:1536 nt
	global_load_dwordx2 v[48:49], v[0:1], off offset:1024 nt
	global_load_dwordx2 v[52:53], v[0:1], off offset:512 nt
	global_load_dwordx2 v[54:55], v[0:1], off nt
	v_lshl_add_u64 v[0:1], s[46:47], 0, v[4:5]
	s_mov_b64 s[0:1], 0x1000
	v_lshl_add_u64 v[4:5], s[48:49], 0, v[4:5]
	s_waitcnt vmcnt(9)
	v_lshl_add_u64 v[56:57], v[0:1], 0, s[0:1]
	v_lshl_add_u64 v[58:59], v[4:5], 0, s[0:1]
	s_movk_i32 s0, 0x1000
	v_add_co_u32_e32 v0, vcc, s0, v0
	v_and_b32_e32 v36, 63, v36
	s_nop 0
	v_addc_co_u32_e32 v1, vcc, 0, v1, vcc
	s_waitcnt vmcnt(8)
	v_add_co_u32_e32 v60, vcc, s0, v4
	global_load_dwordx4 v[0:3], v[0:1], off nt
	s_nop 0
	v_addc_co_u32_e32 v61, vcc, 0, v5, vcc
	global_load_dwordx4 v[4:7], v[60:61], off nt
	global_load_dwordx4 v[8:11], v[56:57], off offset:1024 nt
	global_load_dwordx4 v[12:15], v[56:57], off offset:2048 nt
	global_load_dwordx4 v[16:19], v[58:59], off offset:1024 nt
	global_load_dwordx4 v[20:23], v[58:59], off offset:2048 nt
	global_load_dwordx4 v[24:27], v[56:57], off offset:3072 nt
	global_load_dwordx4 v[28:31], v[58:59], off offset:3072 nt
	v_lshlrev_b64 v[56:57], 12, v[38:39]
	v_lshl_or_b32 v56, v36, 4, v56
	s_ashr_i32 s97, s96, 31
	v_lshl_add_u64 v[36:37], s[50:51], 0, v[56:57]
	s_lshl_b64 s[2:3], s[96:97], 12
	s_mov_b64 s[4:5], 0
	s_movk_i32 s8, 0x7fff
	s_mov_b32 s6, 0x3fb504f3
	v_mov_b32_e32 v39, 0x3727c5ac
	s_mov_b32 s9, 0x800000
.LBB0_2051:
	v_add_u32_e32 v73, s96, v38
	v_cmp_gt_i32_e64 s[0:1], s7, v73
	s_waitcnt vmcnt(8)
	v_lshlrev_b32_e32 v56, 16, v54
	v_and_b32_e32 v57, 0xffff0000, v54
	v_lshlrev_b32_e32 v54, 16, v55
	v_and_b32_e32 v55, 0xffff0000, v55
	v_lshlrev_b32_e32 v58, 16, v50
	v_and_b32_e32 v59, 0xffff0000, v50
	v_lshlrev_b32_e32 v50, 16, v51
	v_and_b32_e32 v51, 0xffff0000, v51
	v_lshlrev_b32_e32 v60, 16, v52
	v_and_b32_e32 v61, 0xffff0000, v52
	v_lshlrev_b32_e32 v52, 16, v53
	v_and_b32_e32 v53, 0xffff0000, v53
	v_lshlrev_b32_e32 v62, 16, v46
	v_and_b32_e32 v63, 0xffff0000, v46
	v_lshlrev_b32_e32 v46, 16, v47
	v_and_b32_e32 v47, 0xffff0000, v47
	v_lshlrev_b32_e32 v64, 16, v48
	v_and_b32_e32 v65, 0xffff0000, v48
	v_lshlrev_b32_e32 v48, 16, v49
	v_and_b32_e32 v49, 0xffff0000, v49
	v_lshlrev_b32_e32 v66, 16, v42
	v_and_b32_e32 v67, 0xffff0000, v42
	v_lshlrev_b32_e32 v42, 16, v43
	v_and_b32_e32 v43, 0xffff0000, v43
	v_lshlrev_b32_e32 v68, 16, v44
	v_and_b32_e32 v69, 0xffff0000, v44
	v_lshlrev_b32_e32 v70, 16, v40
	v_and_b32_e32 v71, 0xffff0000, v40
	v_cndmask_b32_e64 v72, v38, v73, s[0:1]
	v_lshlrev_b32_e32 v44, 16, v45
	v_and_b32_e32 v45, 0xffff0000, v45
	v_lshlrev_b32_e32 v40, 16, v41
	v_and_b32_e32 v41, 0xffff0000, v41
	v_cmp_lt_i32_e32 vcc, s8, v73
	v_pk_fma_f32 v[56:57], v[56:57], s[6:7], v[58:59] op_sel_hi:[1,0,1]
	v_pk_fma_f32 v[50:51], v[54:55], s[6:7], v[50:51] op_sel_hi:[1,0,1]
	v_pk_fma_f32 v[54:55], v[60:61], s[6:7], v[62:63] op_sel_hi:[1,0,1]
	v_pk_fma_f32 v[46:47], v[52:53], s[6:7], v[46:47] op_sel_hi:[1,0,1]
	v_pk_fma_f32 v[52:53], v[64:65], s[6:7], v[66:67] op_sel_hi:[1,0,1]
	v_pk_fma_f32 v[42:43], v[48:49], s[6:7], v[42:43] op_sel_hi:[1,0,1]
	v_pk_fma_f32 v[48:49], v[68:69], s[6:7], v[70:71] op_sel_hi:[1,0,1]
	v_mov_b32_e32 v38, v73
	v_ashrrev_i32_e32 v73, 31, v72
	v_pk_fma_f32 v[40:41], v[44:45], s[6:7], v[40:41] op_sel_hi:[1,0,1]
	v_mov_b32_e32 v44, v56
	v_mov_b32_e32 v45, v54
	v_mov_b32_e32 v58, v57
	v_mov_b32_e32 v59, v55
	v_mov_b32_e32 v64, v52
	v_mov_b32_e32 v65, v48
	v_mov_b32_e32 v66, v53
	v_mov_b32_e32 v67, v49
	v_lshlrev_b64 v[72:73], 11, v[72:73]
	v_mov_b32_e32 v60, v50
	v_mov_b32_e32 v61, v46
	v_mov_b32_e32 v68, v42
	v_mov_b32_e32 v69, v40
	v_pk_add_f32 v[44:45], v[44:45], v[58:59]
	v_pk_add_f32 v[58:59], v[64:65], v[66:67]
	v_lshl_add_u64 v[64:65], v[32:33], 0, v[72:73]
	v_lshl_add_u64 v[66:67], v[34:35], 0, v[72:73]
	v_pk_add_f32 v[44:45], v[60:61], v[44:45]
	v_pk_add_f32 v[58:59], v[68:69], v[58:59]
	global_load_dwordx2 v[60:61], v[64:65], off nt
	global_load_dwordx2 v[68:69], v[64:65], off offset:512 nt
	global_load_dwordx2 v[72:73], v[64:65], off offset:1024 nt
	global_load_dwordx2 v[74:75], v[64:65], off offset:1536 nt
	global_load_dwordx2 v[76:77], v[66:67], off nt
	global_load_dwordx2 v[78:79], v[66:67], off offset:512 nt
	global_load_dwordx2 v[80:81], v[66:67], off offset:1024 nt
	global_load_dwordx2 v[82:83], v[66:67], off offset:1536 nt
	v_mov_b32_e32 v62, v51
	v_mov_b32_e32 v63, v47
	v_pk_add_f32 v[44:45], v[62:63], v[44:45]
	v_mov_b32_e32 v70, v43
	v_mov_b32_e32 v71, v41
	v_add_f32_e32 v44, 0, v44
	v_pk_add_f32 v[58:59], v[70:71], v[58:59]
	v_add_f32_e32 v44, v44, v45
	v_add_f32_e32 v44, v44, v58
	v_add_f32_e32 v44, v44, v59
	s_or_b64 s[4:5], vcc, s[4:5]
	s_nop 0
	v_add_f32_dpp v44, v44, v44 quad_perm:[1,0,3,2] row_mask:0xf bank_mask:0xf bound_ctrl:1
	s_nop 1
	v_add_f32_dpp v44, v44, v44 quad_perm:[2,3,0,1] row_mask:0xf bank_mask:0xf bound_ctrl:1
	s_nop 1
	v_add_f32_dpp v44, v44, v44 row_half_mirror row_mask:0xf bank_mask:0xf bound_ctrl:1
	s_nop 1
	v_add_f32_dpp v44, v44, v44 row_mirror row_mask:0xf bank_mask:0xf bound_ctrl:1
	s_nop 0
	v_readlane_b32 s10, v44, 16
	v_readlane_b32 s11, v44, 48
	v_readlane_b32 s0, v44, 0
	v_readlane_b32 s1, v44, 32
	v_mov_b32_e32 v44, s10
	v_mov_b32_e32 v45, s11
	v_pk_add_f32 v[44:45], s[0:1], v[44:45]
	s_nop 0
	v_add_f32_e32 v44, v44, v45
	v_mul_f32_e32 v44, 0x3a800000, v44
	v_pk_add_f32 v[56:57], v[56:57], v[44:45] op_sel_hi:[1,0] neg_lo:[0,1] neg_hi:[0,1]
	v_pk_add_f32 v[50:51], v[50:51], v[44:45] op_sel_hi:[1,0] neg_lo:[0,1] neg_hi:[0,1]
	v_pk_add_f32 v[54:55], v[54:55], v[44:45] op_sel_hi:[1,0] neg_lo:[0,1] neg_hi:[0,1]
	v_pk_add_f32 v[46:47], v[46:47], v[44:45] op_sel_hi:[1,0] neg_lo:[0,1] neg_hi:[0,1]
	v_pk_add_f32 v[52:53], v[52:53], v[44:45] op_sel_hi:[1,0] neg_lo:[0,1] neg_hi:[0,1]
	v_pk_add_f32 v[42:43], v[42:43], v[44:45] op_sel_hi:[1,0] neg_lo:[0,1] neg_hi:[0,1]
	v_pk_add_f32 v[48:49], v[48:49], v[44:45] op_sel_hi:[1,0] neg_lo:[0,1] neg_hi:[0,1]
	v_pk_add_f32 v[40:41], v[40:41], v[44:45] op_sel_hi:[1,0] neg_lo:[0,1] neg_hi:[0,1]
	v_pk_mul_f32 v[44:45], v[56:57], v[56:57]
	v_pk_mul_f32 v[58:59], v[50:51], v[50:51]
	v_add_f32_e32 v44, v44, v45
	v_add_f32_e32 v44, v58, v44
	v_pk_mul_f32 v[62:63], v[54:55], v[54:55]
	v_add_f32_e32 v44, v59, v44
	v_add_f32_e32 v44, v62, v44
	v_pk_mul_f32 v[64:65], v[46:47], v[46:47]
	v_add_f32_e32 v44, v63, v44
	v_add_f32_e32 v44, v64, v44
	v_pk_mul_f32 v[66:67], v[52:53], v[52:53]
	v_add_f32_e32 v44, v65, v44
	v_add_f32_e32 v44, v66, v44
	v_pk_mul_f32 v[70:71], v[42:43], v[42:43]
	v_add_f32_e32 v44, v67, v44
	v_add_f32_e32 v44, v70, v44
	v_pk_mul_f32 v[84:85], v[48:49], v[48:49]
	v_add_f32_e32 v44, v71, v44
	v_add_f32_e32 v44, v84, v44
	v_pk_mul_f32 v[86:87], v[40:41], v[40:41]
	v_add_f32_e32 v44, v85, v44
	v_add_f32_e32 v44, v86, v44
	v_add_f32_e32 v44, v87, v44
	s_nop 1
	v_add_f32_dpp v44, v44, v44 quad_perm:[1,0,3,2] row_mask:0xf bank_mask:0xf bound_ctrl:1
	s_nop 1
	v_add_f32_dpp v44, v44, v44 quad_perm:[2,3,0,1] row_mask:0xf bank_mask:0xf bound_ctrl:1
	s_nop 1
	v_add_f32_dpp v44, v44, v44 row_half_mirror row_mask:0xf bank_mask:0xf bound_ctrl:1
	s_nop 1
	v_add_f32_dpp v44, v44, v44 row_mirror row_mask:0xf bank_mask:0xf bound_ctrl:1
	s_nop 0
	v_readlane_b32 s10, v44, 16
	v_readlane_b32 s11, v44, 48
	v_readlane_b32 s0, v44, 0
	v_readlane_b32 s1, v44, 32
	v_mov_b32_e32 v44, s10
	v_mov_b32_e32 v45, s11
	v_pk_add_f32 v[44:45], s[0:1], v[44:45]
	s_nop 0
	v_add_f32_e32 v44, v44, v45
	v_fmamk_f32 v44, v44, 0x3a800000, v39
	v_mul_f32_e32 v45, 0x4b800000, v44
	v_cmp_gt_f32_e32 vcc, s9, v44
	s_nop 1
	v_cndmask_b32_e32 v44, v44, v45, vcc
	v_rsq_f32_e32 v44, v44
	s_nop 0
	v_mul_f32_e32 v45, 0x45800000, v44
	v_cndmask_b32_e32 v44, v44, v45, vcc
	v_pk_mul_f32 v[56:57], v[56:57], v[44:45] op_sel_hi:[1,0]
	v_pk_mul_f32 v[50:51], v[50:51], v[44:45] op_sel_hi:[1,0]
	v_pk_mul_f32 v[54:55], v[54:55], v[44:45] op_sel_hi:[1,0]
	v_pk_mul_f32 v[46:47], v[46:47], v[44:45] op_sel_hi:[1,0]
	v_pk_mul_f32 v[52:53], v[52:53], v[44:45] op_sel_hi:[1,0]
	v_pk_mul_f32 v[58:59], v[42:43], v[44:45] op_sel_hi:[1,0]
	v_pk_mul_f32 v[62:63], v[48:49], v[44:45] op_sel_hi:[1,0]
	v_pk_mul_f32 v[64:65], v[40:41], v[44:45] op_sel_hi:[1,0]
	s_waitcnt vmcnt(14)
	v_pk_fma_f32 v[40:41], v[0:1], v[56:57], v[4:5]
	v_pk_fma_f32 v[42:43], v[2:3], v[50:51], v[6:7]
	s_waitcnt vmcnt(11)
	v_pk_fma_f32 v[44:45], v[8:9], v[54:55], v[16:17]
	v_pk_fma_f32 v[46:47], v[10:11], v[46:47], v[18:19]
	s_waitcnt vmcnt(10)
	v_pk_fma_f32 v[48:49], v[12:13], v[52:53], v[20:21]
	v_pk_fma_f32 v[50:51], v[14:15], v[58:59], v[22:23]
	s_waitcnt vmcnt(8)
	v_pk_fma_f32 v[52:53], v[24:25], v[62:63], v[28:29]
	v_pk_fma_f32 v[54:55], v[26:27], v[64:65], v[30:31]
	global_store_dwordx4 v[36:37], v[40:43], off nt
	global_store_dwordx4 v[36:37], v[44:47], off offset:1024 nt
	global_store_dwordx4 v[36:37], v[48:51], off offset:2048 nt
	global_store_dwordx4 v[36:37], v[52:55], off offset:3072 nt
	v_lshl_add_u64 v[36:37], v[36:37], 0, s[2:3]
	s_waitcnt vmcnt(7)
	v_mov_b64_e32 v[50:51], v[76:77]
	s_waitcnt vmcnt(6)
	v_mov_b64_e32 v[46:47], v[78:79]
	s_waitcnt vmcnt(5)
	v_mov_b64_e32 v[42:43], v[80:81]
	s_waitcnt vmcnt(4)
	v_mov_b64_e32 v[40:41], v[82:83]
	v_mov_b64_e32 v[54:55], v[60:61]
	v_mov_b64_e32 v[52:53], v[68:69]
	v_mov_b64_e32 v[48:49], v[72:73]
	v_mov_b64_e32 v[44:45], v[74:75]
	s_andn2_b64 exec, exec, s[4:5]
	s_cbranch_execnz .LBB0_2051
